# GEMM MFMA order only: same-accumulator k0/k1 pairs adjacent (no barrier move)
# speedup vs baseline: 1.0094x; 1.0020x over previous
; #define PG8_STAGE(bufoff, gbase, voff) do { _Pragma("unroll") for (int _i = 0; _i < 2; ++_i) \
;         __builtin_amdgcn_global_load_lds((const unsigned*)((const char*)(gbase) + (voff)[_i]), (PG8_LAS unsigned*)(lds + (bufoff) + ldsw + _i * 8192), 16, 0, 0); } while (0)
; #define PG8_LDA(dst, b, h) do { _Pragma("unroll") for (int m = 0; m < 4; ++m) _Pragma("unroll") for (int k = 0; k < 2; ++k) dst[m][k] = *(const PG8_LAS bf16x8*)(lds + PG8_SA(b, h) + aoff + m * 2048 + k * 1024); } while (0)
; #define PG8_LDB(dst, b, h) do { _Pragma("unroll") for (int n = 0; n < 2; ++n) _Pragma("unroll") for (int k = 0; k < 2; ++k) dst[n][k] = *(const PG8_LAS bf16x8*)(lds + PG8_SB(b, h) + boff + n * 2048 + k * 1024); } while (0)
; #define PG8_WAIT_V(n) asm volatile("s_waitcnt vmcnt(" #n ")" ::: "memory")
; #define PG8_WAIT_L(n) asm volatile("s_waitcnt lgkmcnt(" #n ")" ::: "memory")
; #define PG8_BAR __builtin_amdgcn_s_barrier()
; #define PG8_SCHED __builtin_amdgcn_sched_barrier(0)
; template <class Epi, class Sched, bool ALIGN_EPI = false, bool SP2 = false>
; __device__ __forceinline__ void gemm_phase(PG8_LAS unsigned char* lds, const Gemm g, const Sched& S, const Epi& E) {
;     ...
;         const char* nA = has_next ? (const char*)g.A + (size_t)nxt.pm * tstep : cA; const char* nB = has_next ? (const char*)g.Bt + (size_t)nxt.pn * tstep : cB;
;         for (int t = 0; t < nt; t += 2) {
;             const bool last = (t == nt - 2);
;             const char* a1 = cA + (size_t)(t + 1) * kstepB;
;             const char* a2 = last ? nA : cA + (size_t)(t + 2) * kstepB; const char* b2 = last ? nB : cB + (size_t)(t + 2) * kstepB;
;             const char* a3 = a2 + kstepB; const char* b3 = b2 + kstepB;
;             if (last && has_next) S.a_ready(nxt);
;             if constexpr (SP2) {
;             PG8_LDB(B0, 0, 0); PG8_LDB(B1, 0, 1); PG8_SCHED; PG8_LDA(At, 0, 0); PG8_STAGE(PG8_SA(1, 1), a1 + hstepB, voffA);
;             PG8_WAIT_V(8); PG8_WAIT_L(0); PG8_BAR; PG8_MMA(0, 0, At, B0); PG8_MMA(0, 1, At, B1); PG8_BAR; PG8_SCHED;
;             PG8_LDA(At, 0, 1); PG8_STAGE(PG8_SB(0, 0), b2, voffB); PG8_STAGE(PG8_SB(0, 1), b2 + hstepB, voffB); PG8_STAGE(PG8_SA(0, 0), a2, voffA);
;             PG8_WAIT_V(8); PG8_WAIT_L(0); PG8_BAR; PG8_MMA(1, 0, At, B0); PG8_MMA(1, 1, At, B1); PG8_BAR; PG8_SCHED;
.LBB0_193:
	s_add_i32 s84, s38, 2
	s_add_u32 s39, s36, 0x4000
	s_addc_u32 s40, s37, 0
	s_cmp_eq_u32 s31, s38
	s_cselect_b32 s42, s8, s39
	s_cselect_b32 s43, s9, s40
	s_cselect_b32 s40, s62, s78
	s_cselect_b32 s41, s63, s82
	s_add_u32 s38, s42, 0x8000
	s_addc_u32 s39, s43, 0
	s_add_i32 s90, 0, 0x10000
	s_add_i32 s64, 0, 0x14000
	v_add_u32_e32 v140, s90, v174
	v_add_u32_e32 v161, s64, v174
	ds_read_b128 v[128:131], v140
	ds_read_b128 v[132:135], v140 offset:1024
	ds_read_b128 v[136:139], v140 offset:2048
	ds_read_b128 v[140:143], v140 offset:3072
	ds_read_b128 v[144:147], v161
	ds_read_b128 v[148:151], v161 offset:1024
	ds_read_b128 v[178:181], v161 offset:2048
	ds_read_b128 v[182:185], v161 offset:3072
	v_lshl_add_u64 v[172:173], s[36:37], 0, v[168:169]
	s_add_i32 m0, s21, 0xc000
	ds_read_b128 v[186:189], v177
	ds_read_b128 v[190:193], v177 offset:1024
	ds_read_b128 v[194:197], v177 offset:2048
	ds_read_b128 v[198:201], v177 offset:3072
	ds_read_b128 v[202:205], v177 offset:4096
	ds_read_b128 v[206:209], v177 offset:5120
	ds_read_b128 v[210:213], v177 offset:6144
	ds_read_b128 v[214:217], v177 offset:7168
	global_load_lds_dwordx4 v[172:173], off
	v_lshl_add_u64 v[172:173], s[36:37], 0, v[170:171]
	s_add_i32 m0, s21, 0xe000
	s_nop 0
	global_load_lds_dwordx4 v[172:173], off
	s_waitcnt vmcnt(8)
	s_waitcnt lgkmcnt(0)
	s_barrier
	s_setprio 1
	s_waitcnt lgkmcnt(0)
	v_mfma_f32_16x16x32_bf16 v[124:127], v[128:131], v[186:189], v[124:127]
	v_mfma_f32_16x16x32_bf16 v[124:127], v[132:135], v[190:193], v[124:127]
	v_mfma_f32_16x16x32_bf16 v[120:123], v[136:139], v[186:189], v[120:123]
	v_mfma_f32_16x16x32_bf16 v[120:123], v[140:143], v[190:193], v[120:123]
	v_mfma_f32_16x16x32_bf16 v[108:111], v[128:131], v[194:197], v[108:111]
	v_mfma_f32_16x16x32_bf16 v[108:111], v[132:135], v[198:201], v[108:111]
	v_mfma_f32_16x16x32_bf16 v[104:107], v[136:139], v[194:197], v[104:107]
	v_mfma_f32_16x16x32_bf16 v[104:107], v[140:143], v[198:201], v[104:107]
	v_mfma_f32_16x16x32_bf16 v[92:95], v[128:131], v[202:205], v[92:95]
	v_mfma_f32_16x16x32_bf16 v[92:95], v[132:135], v[206:209], v[92:95]
	v_mfma_f32_16x16x32_bf16 v[88:91], v[136:139], v[202:205], v[88:91]
	v_mfma_f32_16x16x32_bf16 v[88:91], v[140:143], v[206:209], v[88:91]
	v_mfma_f32_16x16x32_bf16 v[76:79], v[128:131], v[210:213], v[76:79]
	v_mfma_f32_16x16x32_bf16 v[76:79], v[132:135], v[214:217], v[76:79]
	v_mfma_f32_16x16x32_bf16 v[72:75], v[136:139], v[210:213], v[72:75]
	v_mfma_f32_16x16x32_bf16 v[72:75], v[140:143], v[214:217], v[72:75]
	s_setprio 0
	s_setprio 1
	v_mfma_f32_16x16x32_bf16 v[116:119], v[144:147], v[186:189], v[116:119]
	v_mfma_f32_16x16x32_bf16 v[116:119], v[148:151], v[190:193], v[116:119]
	v_mfma_f32_16x16x32_bf16 v[112:115], v[178:181], v[186:189], v[112:115]
	v_mfma_f32_16x16x32_bf16 v[112:115], v[182:185], v[190:193], v[112:115]
	v_mfma_f32_16x16x32_bf16 v[100:103], v[144:147], v[194:197], v[100:103]
	v_mfma_f32_16x16x32_bf16 v[100:103], v[148:151], v[198:201], v[100:103]
	v_mfma_f32_16x16x32_bf16 v[96:99], v[178:181], v[194:197], v[96:99]
	v_mfma_f32_16x16x32_bf16 v[96:99], v[182:185], v[198:201], v[96:99]
	v_mfma_f32_16x16x32_bf16 v[84:87], v[144:147], v[202:205], v[84:87]
	v_mfma_f32_16x16x32_bf16 v[84:87], v[148:151], v[206:209], v[84:87]
	v_mfma_f32_16x16x32_bf16 v[80:83], v[178:181], v[202:205], v[80:83]
	v_mfma_f32_16x16x32_bf16 v[80:83], v[182:185], v[206:209], v[80:83]
	v_mfma_f32_16x16x32_bf16 v[68:71], v[144:147], v[210:213], v[68:71]
	v_mfma_f32_16x16x32_bf16 v[68:71], v[148:151], v[214:217], v[68:71]
	v_mfma_f32_16x16x32_bf16 v[64:67], v[178:181], v[210:213], v[64:67]
	v_mfma_f32_16x16x32_bf16 v[64:67], v[182:185], v[214:217], v[64:67]
	s_setprio 0
	s_barrier
	s_add_i32 s65, s90, s20
	v_lshl_add_u64 v[172:173], s[40:41], 0, v[156:157]
	s_mov_b32 m0, s65
	ds_read_b128 v[186:189], v177 offset:16384
	ds_read_b128 v[190:193], v177 offset:17408
	ds_read_b128 v[194:197], v177 offset:18432
	ds_read_b128 v[198:201], v177 offset:19456
	ds_read_b128 v[202:205], v177 offset:20480
	ds_read_b128 v[206:209], v177 offset:21504
	ds_read_b128 v[210:213], v177 offset:22528
	ds_read_b128 v[214:217], v177 offset:23552
	global_load_lds_dwordx4 v[172:173], off
	s_add_i32 m0, s65, 0x2000
	s_add_u32 vcc_lo, s40, 0x4000
	v_lshl_add_u64 v[172:173], s[40:41], 0, v[152:153]
	s_addc_u32 vcc_hi, s41, 0
	s_add_i32 s64, s64, s20
	global_load_lds_dwordx4 v[172:173], off
	v_lshl_add_u64 v[172:173], vcc, 0, v[156:157]
	s_mov_b32 m0, s64
	s_nop 0
	global_load_lds_dwordx4 v[172:173], off
	v_lshl_add_u64 v[172:173], vcc, 0, v[152:153]
	s_add_i32 m0, s64, 0x2000
	s_nop 0
	global_load_lds_dwordx4 v[172:173], off
	v_lshl_add_u64 v[172:173], s[42:43], 0, v[158:159]
	s_mov_b32 m0, s21
	s_nop 0
	global_load_lds_dwordx4 v[172:173], off
	v_lshl_add_u64 v[172:173], s[42:43], 0, v[154:155]
	s_mov_b32 m0, s22
	s_nop 0
	global_load_lds_dwordx4 v[172:173], off
	s_waitcnt vmcnt(8)
	s_waitcnt lgkmcnt(0)
	s_barrier
; #define PG8_STAGE(bufoff, gbase, voff) do { _Pragma("unroll") for (int _i = 0; _i < 2; ++_i) \
;         __builtin_amdgcn_global_load_lds((const unsigned*)((const char*)(gbase) + (voff)[_i]), (PG8_LAS unsigned*)(lds + (bufoff) + ldsw + _i * 8192), 16, 0, 0); } while (0)
; #define PG8_LDA(dst, b, h) do { _Pragma("unroll") for (int m = 0; m < 4; ++m) _Pragma("unroll") for (int k = 0; k < 2; ++k) dst[m][k] = *(const PG8_LAS bf16x8*)(lds + PG8_SA(b, h) + aoff + m * 2048 + k * 1024); } while (0)
; #define PG8_LDB(dst, b, h) do { _Pragma("unroll") for (int n = 0; n < 2; ++n) _Pragma("unroll") for (int k = 0; k < 2; ++k) dst[n][k] = *(const PG8_LAS bf16x8*)(lds + PG8_SB(b, h) + boff + n * 2048 + k * 1024); } while (0)
; #define PG8_MMA(ai, bj, At, Bt) do { __builtin_amdgcn_s_setprio(1); _Pragma("unroll") for (int m = 0; m < 4; ++m) _Pragma("unroll") for (int n = 0; n < 2; ++n) _Pragma("unroll") for (int k = 0; k < 2; ++k) \
;         acc[ai][bj][m][n] = __builtin_amdgcn_mfma_f32_16x16x32_bf16(Bt[n][k], At[m][k], acc[ai][bj][m][n], 0, 0, 0); __builtin_amdgcn_s_setprio(0); } while (0)
; #define PG8_WAIT_V(n) asm volatile("s_waitcnt vmcnt(" #n ")" ::: "memory")
; #define PG8_WAIT_L(n) asm volatile("s_waitcnt lgkmcnt(" #n ")" ::: "memory")
; #define PG8_BAR __builtin_amdgcn_s_barrier()
; #define PG8_SCHED __builtin_amdgcn_sched_barrier(0)
; template <class Epi, class Sched, bool ALIGN_EPI = false, bool SP2 = false>
; __device__ __forceinline__ void gemm_phase(PG8_LAS unsigned char* lds, const Gemm g, const Sched& S, const Epi& E) {
;     ...
;             PG8_WAIT_V(8); PG8_WAIT_L(0); PG8_BAR; PG8_MMA(1, 0, At, B0); PG8_MMA(1, 1, At, B1); PG8_BAR; PG8_SCHED;
;             PG8_LDB(B0, 1, 0); PG8_LDB(B1, 1, 1); PG8_SCHED; PG8_LDA(At, 1, 0); PG8_STAGE(PG8_SA(0, 1), a2 + hstepB, voffA);
;             PG8_WAIT_V(8); PG8_WAIT_L(0); PG8_BAR; PG8_MMA(0, 0, At, B0); PG8_MMA(0, 1, At, B1); PG8_BAR; PG8_SCHED;
;             PG8_LDA(At, 1, 1); PG8_STAGE(PG8_SB(1, 0), b3, voffB); PG8_STAGE(PG8_SB(1, 1), b3 + hstepB, voffB); PG8_STAGE(PG8_SA(1, 0), a3, voffA);
	s_setprio 1
	s_waitcnt lgkmcnt(0)
	v_mfma_f32_16x16x32_bf16 v[60:63], v[128:131], v[186:189], v[60:63]
	v_mfma_f32_16x16x32_bf16 v[60:63], v[132:135], v[190:193], v[60:63]
	v_mfma_f32_16x16x32_bf16 v[56:59], v[136:139], v[186:189], v[56:59]
	v_mfma_f32_16x16x32_bf16 v[56:59], v[140:143], v[190:193], v[56:59]
	v_mfma_f32_16x16x32_bf16 v[44:47], v[128:131], v[194:197], v[44:47]
	v_mfma_f32_16x16x32_bf16 v[44:47], v[132:135], v[198:201], v[44:47]
	v_mfma_f32_16x16x32_bf16 v[40:43], v[136:139], v[194:197], v[40:43]
	v_mfma_f32_16x16x32_bf16 v[40:43], v[140:143], v[198:201], v[40:43]
	v_mfma_f32_16x16x32_bf16 v[28:31], v[128:131], v[202:205], v[28:31]
	v_mfma_f32_16x16x32_bf16 v[28:31], v[132:135], v[206:209], v[28:31]
	v_mfma_f32_16x16x32_bf16 v[24:27], v[136:139], v[202:205], v[24:27]
	v_mfma_f32_16x16x32_bf16 v[24:27], v[140:143], v[206:209], v[24:27]
	v_mfma_f32_16x16x32_bf16 v[12:15], v[128:131], v[210:213], v[12:15]
	v_mfma_f32_16x16x32_bf16 v[12:15], v[132:135], v[214:217], v[12:15]
	v_mfma_f32_16x16x32_bf16 v[8:11], v[136:139], v[210:213], v[8:11]
	v_mfma_f32_16x16x32_bf16 v[8:11], v[140:143], v[214:217], v[8:11]
	s_setprio 0
	s_setprio 1
	v_mfma_f32_16x16x32_bf16 v[52:55], v[144:147], v[186:189], v[52:55]
	v_mfma_f32_16x16x32_bf16 v[52:55], v[148:151], v[190:193], v[52:55]
	v_mfma_f32_16x16x32_bf16 v[48:51], v[178:181], v[186:189], v[48:51]
	v_mfma_f32_16x16x32_bf16 v[48:51], v[182:185], v[190:193], v[48:51]
	v_mfma_f32_16x16x32_bf16 v[36:39], v[144:147], v[194:197], v[36:39]
	v_mfma_f32_16x16x32_bf16 v[36:39], v[148:151], v[198:201], v[36:39]
	v_mfma_f32_16x16x32_bf16 v[32:35], v[178:181], v[194:197], v[32:35]
	v_mfma_f32_16x16x32_bf16 v[32:35], v[182:185], v[198:201], v[32:35]
	v_mfma_f32_16x16x32_bf16 v[20:23], v[144:147], v[202:205], v[20:23]
	v_mfma_f32_16x16x32_bf16 v[20:23], v[148:151], v[206:209], v[20:23]
	v_mfma_f32_16x16x32_bf16 v[16:19], v[178:181], v[202:205], v[16:19]
	v_mfma_f32_16x16x32_bf16 v[16:19], v[182:185], v[206:209], v[16:19]
	v_mfma_f32_16x16x32_bf16 v[4:7], v[144:147], v[210:213], v[4:7]
	v_mfma_f32_16x16x32_bf16 v[4:7], v[148:151], v[214:217], v[4:7]
	v_mfma_f32_16x16x32_bf16 v[0:3], v[178:181], v[210:213], v[0:3]
	v_mfma_f32_16x16x32_bf16 v[0:3], v[182:185], v[214:217], v[0:3]
	s_setprio 0
	s_barrier
	s_add_i32 s64, 0, 0x18000
	s_add_i32 s65, 0, 0x1c000
	v_add_u32_e32 v140, s64, v174
	v_add_u32_e32 v161, s65, v174
	ds_read_b128 v[128:131], v140
	ds_read_b128 v[132:135], v140 offset:1024
	ds_read_b128 v[136:139], v140 offset:2048
	ds_read_b128 v[140:143], v140 offset:3072
	ds_read_b128 v[144:147], v161
	ds_read_b128 v[148:151], v161 offset:1024
	ds_read_b128 v[178:181], v161 offset:2048
	ds_read_b128 v[182:185], v161 offset:3072
	s_add_u32 s42, s42, 0x4000
	s_addc_u32 s43, s43, 0
	s_mov_b32 m0, s23
	v_lshl_add_u64 v[172:173], s[42:43], 0, v[158:159]
	ds_read_b128 v[186:189], v177 offset:32768
	ds_read_b128 v[190:193], v177 offset:33792
	ds_read_b128 v[194:197], v177 offset:34816
	ds_read_b128 v[198:201], v177 offset:35840
	ds_read_b128 v[202:205], v177 offset:36864
	ds_read_b128 v[206:209], v177 offset:37888
	ds_read_b128 v[210:213], v177 offset:38912
	ds_read_b128 v[214:217], v177 offset:39936
	global_load_lds_dwordx4 v[172:173], off
	v_lshl_add_u64 v[172:173], s[42:43], 0, v[154:155]
	s_mov_b32 m0, s24
	s_nop 0
	global_load_lds_dwordx4 v[172:173], off
	s_waitcnt vmcnt(8)
	s_waitcnt lgkmcnt(0)
	s_barrier
	s_setprio 1
	s_waitcnt lgkmcnt(0)
	v_mfma_f32_16x16x32_bf16 v[124:127], v[128:131], v[186:189], v[124:127]
	v_mfma_f32_16x16x32_bf16 v[124:127], v[132:135], v[190:193], v[124:127]
	v_mfma_f32_16x16x32_bf16 v[120:123], v[136:139], v[186:189], v[120:123]
	v_mfma_f32_16x16x32_bf16 v[120:123], v[140:143], v[190:193], v[120:123]
	v_mfma_f32_16x16x32_bf16 v[108:111], v[128:131], v[194:197], v[108:111]
	v_mfma_f32_16x16x32_bf16 v[108:111], v[132:135], v[198:201], v[108:111]
	v_mfma_f32_16x16x32_bf16 v[104:107], v[136:139], v[194:197], v[104:107]
	v_mfma_f32_16x16x32_bf16 v[104:107], v[140:143], v[198:201], v[104:107]
	v_mfma_f32_16x16x32_bf16 v[92:95], v[128:131], v[202:205], v[92:95]
	v_mfma_f32_16x16x32_bf16 v[92:95], v[132:135], v[206:209], v[92:95]
	v_mfma_f32_16x16x32_bf16 v[88:91], v[136:139], v[202:205], v[88:91]
	v_mfma_f32_16x16x32_bf16 v[88:91], v[140:143], v[206:209], v[88:91]
	v_mfma_f32_16x16x32_bf16 v[76:79], v[128:131], v[210:213], v[76:79]
	v_mfma_f32_16x16x32_bf16 v[76:79], v[132:135], v[214:217], v[76:79]
	v_mfma_f32_16x16x32_bf16 v[72:75], v[136:139], v[210:213], v[72:75]
	v_mfma_f32_16x16x32_bf16 v[72:75], v[140:143], v[214:217], v[72:75]
	s_setprio 0
	s_setprio 1
	v_mfma_f32_16x16x32_bf16 v[116:119], v[144:147], v[186:189], v[116:119]
	v_mfma_f32_16x16x32_bf16 v[116:119], v[148:151], v[190:193], v[116:119]
	v_mfma_f32_16x16x32_bf16 v[112:115], v[178:181], v[186:189], v[112:115]
	v_mfma_f32_16x16x32_bf16 v[112:115], v[182:185], v[190:193], v[112:115]
	v_mfma_f32_16x16x32_bf16 v[100:103], v[144:147], v[194:197], v[100:103]
	v_mfma_f32_16x16x32_bf16 v[100:103], v[148:151], v[198:201], v[100:103]
	v_mfma_f32_16x16x32_bf16 v[96:99], v[178:181], v[194:197], v[96:99]
	v_mfma_f32_16x16x32_bf16 v[96:99], v[182:185], v[198:201], v[96:99]
	v_mfma_f32_16x16x32_bf16 v[84:87], v[144:147], v[202:205], v[84:87]
	v_mfma_f32_16x16x32_bf16 v[84:87], v[148:151], v[206:209], v[84:87]
	v_mfma_f32_16x16x32_bf16 v[80:83], v[178:181], v[202:205], v[80:83]
	v_mfma_f32_16x16x32_bf16 v[80:83], v[182:185], v[206:209], v[80:83]
	v_mfma_f32_16x16x32_bf16 v[68:71], v[144:147], v[210:213], v[68:71]
	v_mfma_f32_16x16x32_bf16 v[68:71], v[148:151], v[214:217], v[68:71]
	v_mfma_f32_16x16x32_bf16 v[64:67], v[178:181], v[210:213], v[64:67]
	v_mfma_f32_16x16x32_bf16 v[64:67], v[182:185], v[214:217], v[64:67]
	s_setprio 0
	s_barrier
; #define PG8_STAGE(bufoff, gbase, voff) do { _Pragma("unroll") for (int _i = 0; _i < 2; ++_i) \
;         __builtin_amdgcn_global_load_lds((const unsigned*)((const char*)(gbase) + (voff)[_i]), (PG8_LAS unsigned*)(lds + (bufoff) + ldsw + _i * 8192), 16, 0, 0); } while (0)
; #define PG8_LDA(dst, b, h) do { _Pragma("unroll") for (int m = 0; m < 4; ++m) _Pragma("unroll") for (int k = 0; k < 2; ++k) dst[m][k] = *(const PG8_LAS bf16x8*)(lds + PG8_SA(b, h) + aoff + m * 2048 + k * 1024); } while (0)
; #define PG8_MMA(ai, bj, At, Bt) do { __builtin_amdgcn_s_setprio(1); _Pragma("unroll") for (int m = 0; m < 4; ++m) _Pragma("unroll") for (int n = 0; n < 2; ++n) _Pragma("unroll") for (int k = 0; k < 2; ++k) \
;         acc[ai][bj][m][n] = __builtin_amdgcn_mfma_f32_16x16x32_bf16(Bt[n][k], At[m][k], acc[ai][bj][m][n], 0, 0, 0); __builtin_amdgcn_s_setprio(0); } while (0)
; #define PG8_WAIT_V(n) asm volatile("s_waitcnt vmcnt(" #n ")" ::: "memory")
; #define PG8_WAIT_L(n) asm volatile("s_waitcnt lgkmcnt(" #n ")" ::: "memory")
; #define PG8_BAR __builtin_amdgcn_s_barrier()
; #define PG8_SCHED __builtin_amdgcn_sched_barrier(0)
; template <class Epi, class Sched, bool ALIGN_EPI = false, bool SP2 = false>
; __device__ __forceinline__ void gemm_phase(PG8_LAS unsigned char* lds, const Gemm g, const Sched& S, const Epi& E) {
;     ...
;             PG8_LDA(At, 1, 1); PG8_STAGE(PG8_SB(1, 0), b3, voffB); PG8_STAGE(PG8_SB(1, 1), b3 + hstepB, voffB); PG8_STAGE(PG8_SA(1, 0), a3, voffA);
;             PG8_WAIT_V(8); PG8_WAIT_L(0); PG8_BAR; PG8_MMA(1, 0, At, B0); PG8_MMA(1, 1, At, B1); PG8_BAR; PG8_SCHED;
	s_add_u32 s42, s40, 0x8000
	s_addc_u32 s43, s41, 0
	s_add_i32 s64, s64, s20
	v_lshl_add_u64 v[172:173], s[42:43], 0, v[156:157]
	s_mov_b32 m0, s64
	ds_read_b128 v[186:189], v177 offset:49152
	ds_read_b128 v[190:193], v177 offset:50176
	ds_read_b128 v[194:197], v177 offset:51200
	ds_read_b128 v[198:201], v177 offset:52224
	ds_read_b128 v[202:205], v177 offset:53248
	ds_read_b128 v[206:209], v177 offset:54272
	ds_read_b128 v[210:213], v177 offset:55296
	ds_read_b128 v[214:217], v177 offset:56320
	global_load_lds_dwordx4 v[172:173], off
	s_add_i32 m0, s64, 0x2000
	s_add_u32 s40, s40, 0xc000
	v_lshl_add_u64 v[172:173], s[42:43], 0, v[152:153]
	s_addc_u32 s41, s41, 0
	s_add_i32 s42, s65, s20
	global_load_lds_dwordx4 v[172:173], off
	v_lshl_add_u64 v[172:173], s[40:41], 0, v[156:157]
	s_mov_b32 m0, s42
	s_nop 0
	global_load_lds_dwordx4 v[172:173], off
	v_lshl_add_u64 v[172:173], s[40:41], 0, v[152:153]
	s_add_i32 m0, s42, 0x2000
	s_nop 0
	global_load_lds_dwordx4 v[172:173], off
	v_lshl_add_u64 v[172:173], s[38:39], 0, v[158:159]
	s_mov_b32 m0, s29
	s_nop 0
	global_load_lds_dwordx4 v[172:173], off
	v_lshl_add_u64 v[172:173], s[38:39], 0, v[154:155]
	s_mov_b32 m0, s30
	s_nop 0
	global_load_lds_dwordx4 v[172:173], off
	s_waitcnt vmcnt(8)
	s_waitcnt lgkmcnt(0)
	s_barrier
	s_setprio 1
	s_waitcnt lgkmcnt(0)
	v_mfma_f32_16x16x32_bf16 v[60:63], v[128:131], v[186:189], v[60:63]
	v_mfma_f32_16x16x32_bf16 v[60:63], v[132:135], v[190:193], v[60:63]
	v_mfma_f32_16x16x32_bf16 v[56:59], v[136:139], v[186:189], v[56:59]
	v_mfma_f32_16x16x32_bf16 v[56:59], v[140:143], v[190:193], v[56:59]
	v_mfma_f32_16x16x32_bf16 v[44:47], v[128:131], v[194:197], v[44:47]
	v_mfma_f32_16x16x32_bf16 v[44:47], v[132:135], v[198:201], v[44:47]
	v_mfma_f32_16x16x32_bf16 v[40:43], v[136:139], v[194:197], v[40:43]
	v_mfma_f32_16x16x32_bf16 v[40:43], v[140:143], v[198:201], v[40:43]
	v_mfma_f32_16x16x32_bf16 v[28:31], v[128:131], v[202:205], v[28:31]
	v_mfma_f32_16x16x32_bf16 v[28:31], v[132:135], v[206:209], v[28:31]
	v_mfma_f32_16x16x32_bf16 v[24:27], v[136:139], v[202:205], v[24:27]
	v_mfma_f32_16x16x32_bf16 v[24:27], v[140:143], v[206:209], v[24:27]
	v_mfma_f32_16x16x32_bf16 v[12:15], v[128:131], v[210:213], v[12:15]
	v_mfma_f32_16x16x32_bf16 v[12:15], v[132:135], v[214:217], v[12:15]
	v_mfma_f32_16x16x32_bf16 v[8:11], v[136:139], v[210:213], v[8:11]
	v_mfma_f32_16x16x32_bf16 v[8:11], v[140:143], v[214:217], v[8:11]
	s_setprio 0
	s_setprio 1
	v_mfma_f32_16x16x32_bf16 v[52:55], v[144:147], v[186:189], v[52:55]
	v_mfma_f32_16x16x32_bf16 v[52:55], v[148:151], v[190:193], v[52:55]
	v_mfma_f32_16x16x32_bf16 v[48:51], v[178:181], v[186:189], v[48:51]
	v_mfma_f32_16x16x32_bf16 v[48:51], v[182:185], v[190:193], v[48:51]
	v_mfma_f32_16x16x32_bf16 v[36:39], v[144:147], v[194:197], v[36:39]
	v_mfma_f32_16x16x32_bf16 v[36:39], v[148:151], v[198:201], v[36:39]
	v_mfma_f32_16x16x32_bf16 v[32:35], v[178:181], v[194:197], v[32:35]
	v_mfma_f32_16x16x32_bf16 v[32:35], v[182:185], v[198:201], v[32:35]
	v_mfma_f32_16x16x32_bf16 v[20:23], v[144:147], v[202:205], v[20:23]
	v_mfma_f32_16x16x32_bf16 v[20:23], v[148:151], v[206:209], v[20:23]
	v_mfma_f32_16x16x32_bf16 v[16:19], v[178:181], v[202:205], v[16:19]
	v_mfma_f32_16x16x32_bf16 v[16:19], v[182:185], v[206:209], v[16:19]
	v_mfma_f32_16x16x32_bf16 v[4:7], v[144:147], v[210:213], v[4:7]
	v_mfma_f32_16x16x32_bf16 v[4:7], v[148:151], v[214:217], v[4:7]
	v_mfma_f32_16x16x32_bf16 v[0:3], v[178:181], v[210:213], v[0:3]
	v_mfma_f32_16x16x32_bf16 v[0:3], v[182:185], v[214:217], v[0:3]
	s_setprio 0
	s_barrier
	s_add_u32 s36, s36, 0x10000
	s_addc_u32 s37, s37, 0
	s_add_u32 s78, s78, 0x10000
	s_addc_u32 s82, s82, 0
	s_cmp_ge_u32 s84, s26
	s_mov_b32 s38, s84
	s_cbranch_scc0 .LBB0_193
	s_and_b64 vcc, exec, s[60:61]
	s_cbranch_vccz .LBB0_196
	s_barrier

; #define PG8_STAGE(bufoff, gbase, voff) do { _Pragma("unroll") for (int _i = 0; _i < 2; ++_i) \
;         __builtin_amdgcn_global_load_lds((const unsigned*)((const char*)(gbase) + (voff)[_i]), (PG8_LAS unsigned*)(lds + (bufoff) + ldsw + _i * 8192), 16, 0, 0); } while (0)
; #define PG8_LDA(dst, b, h) do { _Pragma("unroll") for (int m = 0; m < 4; ++m) _Pragma("unroll") for (int k = 0; k < 2; ++k) dst[m][k] = *(const PG8_LAS bf16x8*)(lds + PG8_SA(b, h) + aoff + m * 2048 + k * 1024); } while (0)
; #define PG8_LDB(dst, b, h) do { _Pragma("unroll") for (int n = 0; n < 2; ++n) _Pragma("unroll") for (int k = 0; k < 2; ++k) dst[n][k] = *(const PG8_LAS bf16x8*)(lds + PG8_SB(b, h) + boff + n * 2048 + k * 1024); } while (0)
; #define PG8_WAIT_V(n) asm volatile("s_waitcnt vmcnt(" #n ")" ::: "memory")
; #define PG8_WAIT_L(n) asm volatile("s_waitcnt lgkmcnt(" #n ")" ::: "memory")
; #define PG8_BAR __builtin_amdgcn_s_barrier()
; #define PG8_SCHED __builtin_amdgcn_sched_barrier(0)
; template <class Epi, class Sched, bool ALIGN_EPI = false, bool SP2 = false>
; __device__ __forceinline__ void gemm_phase(PG8_LAS unsigned char* lds, const Gemm g, const Sched& S, const Epi& E) {
;     ...
;         const char* nA = has_next ? (const char*)g.A + (size_t)nxt.pm * tstep : cA; const char* nB = has_next ? (const char*)g.Bt + (size_t)nxt.pn * tstep : cB;
;         for (int t = 0; t < nt; t += 2) {
;             const bool last = (t == nt - 2);
;             const char* a1 = cA + (size_t)(t + 1) * kstepB;
;             const char* a2 = last ? nA : cA + (size_t)(t + 2) * kstepB; const char* b2 = last ? nB : cB + (size_t)(t + 2) * kstepB;
;             const char* a3 = a2 + kstepB; const char* b3 = b2 + kstepB;
;             if (last && has_next) S.a_ready(nxt);
;             if constexpr (SP2) {
;             PG8_LDB(B0, 0, 0); PG8_LDB(B1, 0, 1); PG8_SCHED; PG8_LDA(At, 0, 0); PG8_STAGE(PG8_SA(1, 1), a1 + hstepB, voffA);
;             PG8_WAIT_V(8); PG8_WAIT_L(0); PG8_BAR; PG8_MMA(0, 0, At, B0); PG8_MMA(0, 1, At, B1); PG8_BAR; PG8_SCHED;
;             PG8_LDA(At, 0, 1); PG8_STAGE(PG8_SB(0, 0), b2, voffB); PG8_STAGE(PG8_SB(0, 1), b2 + hstepB, voffB); PG8_STAGE(PG8_SA(0, 0), a2, voffA);
;             PG8_WAIT_V(8); PG8_WAIT_L(0); PG8_BAR; PG8_MMA(1, 0, At, B0); PG8_MMA(1, 1, At, B1); PG8_BAR; PG8_SCHED;
.LBB0_232:
	s_add_u32 s31, s36, 0x4000
	s_addc_u32 s38, s37, 0
	s_cmp_eq_u32 s30, 28
	s_cselect_b32 s42, s26, s31
	s_cselect_b32 s43, s13, s38
	s_cselect_b32 s40, s27, s28
	s_cselect_b32 s41, s11, s29
	s_add_u32 s38, s42, 0x8000
	s_addc_u32 s39, s43, 0
	s_add_i32 s31, 0, 0x10000
	s_add_i32 s60, 0, 0x14000
	v_add_u32_e32 v152, s31, v169
	v_add_u32_e32 v175, s60, v169
	ds_read_b128 v[128:131], v152
	ds_read_b128 v[132:135], v152 offset:1024
	ds_read_b128 v[148:151], v152 offset:2048
	ds_read_b128 v[152:155], v152 offset:3072
	ds_read_b128 v[156:159], v175
	ds_read_b128 v[160:163], v175 offset:1024
	ds_read_b128 v[164:167], v175 offset:2048
	ds_read_b128 v[176:179], v175 offset:3072
	v_lshl_add_u64 v[212:213], s[36:37], 0, v[144:145]
	s_add_i32 m0, s17, 0xc000
	ds_read_b128 v[180:183], v174
	ds_read_b128 v[184:187], v174 offset:1024
	ds_read_b128 v[188:191], v174 offset:2048
	ds_read_b128 v[192:195], v174 offset:3072
	ds_read_b128 v[196:199], v174 offset:4096
	ds_read_b128 v[200:203], v174 offset:5120
	ds_read_b128 v[204:207], v174 offset:6144
	ds_read_b128 v[208:211], v174 offset:7168
	global_load_lds_dwordx4 v[212:213], off
	v_lshl_add_u64 v[212:213], s[36:37], 0, v[146:147]
	s_add_i32 m0, s17, 0xe000
	s_nop 0
	global_load_lds_dwordx4 v[212:213], off
	s_waitcnt vmcnt(8)
	s_waitcnt lgkmcnt(0)
	s_barrier
	s_setprio 1
	s_waitcnt lgkmcnt(0)
	v_mfma_f32_16x16x32_bf16 v[124:127], v[128:131], v[180:183], v[124:127]
	v_mfma_f32_16x16x32_bf16 v[124:127], v[132:135], v[184:187], v[124:127]
	v_mfma_f32_16x16x32_bf16 v[120:123], v[148:151], v[180:183], v[120:123]
	v_mfma_f32_16x16x32_bf16 v[120:123], v[152:155], v[184:187], v[120:123]
	v_mfma_f32_16x16x32_bf16 v[108:111], v[128:131], v[188:191], v[108:111]
	v_mfma_f32_16x16x32_bf16 v[108:111], v[132:135], v[192:195], v[108:111]
	v_mfma_f32_16x16x32_bf16 v[104:107], v[148:151], v[188:191], v[104:107]
	v_mfma_f32_16x16x32_bf16 v[104:107], v[152:155], v[192:195], v[104:107]
	v_mfma_f32_16x16x32_bf16 v[92:95], v[128:131], v[196:199], v[92:95]
	v_mfma_f32_16x16x32_bf16 v[92:95], v[132:135], v[200:203], v[92:95]
	v_mfma_f32_16x16x32_bf16 v[88:91], v[148:151], v[196:199], v[88:91]
	v_mfma_f32_16x16x32_bf16 v[88:91], v[152:155], v[200:203], v[88:91]
	v_mfma_f32_16x16x32_bf16 v[76:79], v[128:131], v[204:207], v[76:79]
	v_mfma_f32_16x16x32_bf16 v[76:79], v[132:135], v[208:211], v[76:79]
	v_mfma_f32_16x16x32_bf16 v[72:75], v[148:151], v[204:207], v[72:75]
	v_mfma_f32_16x16x32_bf16 v[72:75], v[152:155], v[208:211], v[72:75]
	s_setprio 0
	s_setprio 1
	v_mfma_f32_16x16x32_bf16 v[116:119], v[156:159], v[180:183], v[116:119]
	v_mfma_f32_16x16x32_bf16 v[116:119], v[160:163], v[184:187], v[116:119]
	v_mfma_f32_16x16x32_bf16 v[112:115], v[164:167], v[180:183], v[112:115]
	v_mfma_f32_16x16x32_bf16 v[112:115], v[176:179], v[184:187], v[112:115]
	v_mfma_f32_16x16x32_bf16 v[100:103], v[156:159], v[188:191], v[100:103]
	v_mfma_f32_16x16x32_bf16 v[100:103], v[160:163], v[192:195], v[100:103]
	v_mfma_f32_16x16x32_bf16 v[96:99], v[164:167], v[188:191], v[96:99]
	v_mfma_f32_16x16x32_bf16 v[96:99], v[176:179], v[192:195], v[96:99]
	v_mfma_f32_16x16x32_bf16 v[84:87], v[156:159], v[196:199], v[84:87]
	v_mfma_f32_16x16x32_bf16 v[84:87], v[160:163], v[200:203], v[84:87]
	v_mfma_f32_16x16x32_bf16 v[80:83], v[164:167], v[196:199], v[80:83]
	v_mfma_f32_16x16x32_bf16 v[80:83], v[176:179], v[200:203], v[80:83]
	v_mfma_f32_16x16x32_bf16 v[68:71], v[156:159], v[204:207], v[68:71]
	v_mfma_f32_16x16x32_bf16 v[68:71], v[160:163], v[208:211], v[68:71]
	v_mfma_f32_16x16x32_bf16 v[64:67], v[164:167], v[204:207], v[64:67]
	v_mfma_f32_16x16x32_bf16 v[64:67], v[176:179], v[208:211], v[64:67]
	s_setprio 0
	s_barrier
	s_add_i32 s31, s31, s14
	v_lshl_add_u64 v[212:213], s[40:41], 0, v[220:221]
	s_mov_b32 m0, s31
	ds_read_b128 v[180:183], v174 offset:16384
	ds_read_b128 v[184:187], v174 offset:17408
	ds_read_b128 v[188:191], v174 offset:18432
	ds_read_b128 v[192:195], v174 offset:19456
	ds_read_b128 v[196:199], v174 offset:20480
	ds_read_b128 v[200:203], v174 offset:21504
	ds_read_b128 v[204:207], v174 offset:22528
	ds_read_b128 v[208:211], v174 offset:23552
	global_load_lds_dwordx4 v[212:213], off
	s_add_i32 m0, s31, 0x2000
	s_add_u32 s44, s40, 0x4000
	v_lshl_add_u64 v[212:213], s[40:41], 0, v[136:137]
	s_addc_u32 s45, s41, 0
	s_add_i32 s31, s60, s14
	global_load_lds_dwordx4 v[212:213], off
	v_lshl_add_u64 v[212:213], s[44:45], 0, v[220:221]
	s_mov_b32 m0, s31
	s_nop 0
	global_load_lds_dwordx4 v[212:213], off
	v_lshl_add_u64 v[212:213], s[44:45], 0, v[136:137]
	s_add_i32 m0, s31, 0x2000
	s_nop 0
	global_load_lds_dwordx4 v[212:213], off
	v_lshl_add_u64 v[212:213], s[42:43], 0, v[140:141]
	s_mov_b32 m0, s17
	s_nop 0
	global_load_lds_dwordx4 v[212:213], off
	v_lshl_add_u64 v[212:213], s[42:43], 0, v[138:139]
	s_mov_b32 m0, s18
	s_nop 0
	global_load_lds_dwordx4 v[212:213], off
	s_waitcnt vmcnt(8)
	s_waitcnt lgkmcnt(0)
	s_barrier
; #define PG8_STAGE(bufoff, gbase, voff) do { _Pragma("unroll") for (int _i = 0; _i < 2; ++_i) \
;         __builtin_amdgcn_global_load_lds((const unsigned*)((const char*)(gbase) + (voff)[_i]), (PG8_LAS unsigned*)(lds + (bufoff) + ldsw + _i * 8192), 16, 0, 0); } while (0)
; #define PG8_LDA(dst, b, h) do { _Pragma("unroll") for (int m = 0; m < 4; ++m) _Pragma("unroll") for (int k = 0; k < 2; ++k) dst[m][k] = *(const PG8_LAS bf16x8*)(lds + PG8_SA(b, h) + aoff + m * 2048 + k * 1024); } while (0)
; #define PG8_LDB(dst, b, h) do { _Pragma("unroll") for (int n = 0; n < 2; ++n) _Pragma("unroll") for (int k = 0; k < 2; ++k) dst[n][k] = *(const PG8_LAS bf16x8*)(lds + PG8_SB(b, h) + boff + n * 2048 + k * 1024); } while (0)
; #define PG8_MMA(ai, bj, At, Bt) do { __builtin_amdgcn_s_setprio(1); _Pragma("unroll") for (int m = 0; m < 4; ++m) _Pragma("unroll") for (int n = 0; n < 2; ++n) _Pragma("unroll") for (int k = 0; k < 2; ++k) \
;         acc[ai][bj][m][n] = __builtin_amdgcn_mfma_f32_16x16x32_bf16(Bt[n][k], At[m][k], acc[ai][bj][m][n], 0, 0, 0); __builtin_amdgcn_s_setprio(0); } while (0)
; #define PG8_WAIT_V(n) asm volatile("s_waitcnt vmcnt(" #n ")" ::: "memory")
; #define PG8_WAIT_L(n) asm volatile("s_waitcnt lgkmcnt(" #n ")" ::: "memory")
; #define PG8_BAR __builtin_amdgcn_s_barrier()
; #define PG8_SCHED __builtin_amdgcn_sched_barrier(0)
; template <class Epi, class Sched, bool ALIGN_EPI = false, bool SP2 = false>
; __device__ __forceinline__ void gemm_phase(PG8_LAS unsigned char* lds, const Gemm g, const Sched& S, const Epi& E) {
;     ...
;             PG8_WAIT_V(8); PG8_WAIT_L(0); PG8_BAR; PG8_MMA(1, 0, At, B0); PG8_MMA(1, 1, At, B1); PG8_BAR; PG8_SCHED;
;             PG8_LDB(B0, 1, 0); PG8_LDB(B1, 1, 1); PG8_SCHED; PG8_LDA(At, 1, 0); PG8_STAGE(PG8_SA(0, 1), a2 + hstepB, voffA);
;             PG8_WAIT_V(8); PG8_WAIT_L(0); PG8_BAR; PG8_MMA(0, 0, At, B0); PG8_MMA(0, 1, At, B1); PG8_BAR; PG8_SCHED;
;             PG8_LDA(At, 1, 1); PG8_STAGE(PG8_SB(1, 0), b3, voffB); PG8_STAGE(PG8_SB(1, 1), b3 + hstepB, voffB); PG8_STAGE(PG8_SA(1, 0), a3, voffA);
	s_setprio 1
	s_waitcnt lgkmcnt(0)
	v_mfma_f32_16x16x32_bf16 v[60:63], v[128:131], v[180:183], v[60:63]
	v_mfma_f32_16x16x32_bf16 v[60:63], v[132:135], v[184:187], v[60:63]
	v_mfma_f32_16x16x32_bf16 v[56:59], v[148:151], v[180:183], v[56:59]
	v_mfma_f32_16x16x32_bf16 v[56:59], v[152:155], v[184:187], v[56:59]
	v_mfma_f32_16x16x32_bf16 v[48:51], v[128:131], v[188:191], v[48:51]
	v_mfma_f32_16x16x32_bf16 v[48:51], v[132:135], v[192:195], v[48:51]
	v_mfma_f32_16x16x32_bf16 v[40:43], v[148:151], v[188:191], v[40:43]
	v_mfma_f32_16x16x32_bf16 v[40:43], v[152:155], v[192:195], v[40:43]
	v_mfma_f32_16x16x32_bf16 v[32:35], v[128:131], v[196:199], v[32:35]
	v_mfma_f32_16x16x32_bf16 v[32:35], v[132:135], v[200:203], v[32:35]
	v_mfma_f32_16x16x32_bf16 v[24:27], v[148:151], v[196:199], v[24:27]
	v_mfma_f32_16x16x32_bf16 v[24:27], v[152:155], v[200:203], v[24:27]
	v_mfma_f32_16x16x32_bf16 v[16:19], v[128:131], v[204:207], v[16:19]
	v_mfma_f32_16x16x32_bf16 v[16:19], v[132:135], v[208:211], v[16:19]
	v_mfma_f32_16x16x32_bf16 v[8:11], v[148:151], v[204:207], v[8:11]
	v_mfma_f32_16x16x32_bf16 v[8:11], v[152:155], v[208:211], v[8:11]
	s_setprio 0
	s_setprio 1
	v_mfma_f32_16x16x32_bf16 v[52:55], v[156:159], v[180:183], v[52:55]
	v_mfma_f32_16x16x32_bf16 v[52:55], v[160:163], v[184:187], v[52:55]
	v_mfma_f32_16x16x32_bf16 v[44:47], v[164:167], v[180:183], v[44:47]
	v_mfma_f32_16x16x32_bf16 v[44:47], v[176:179], v[184:187], v[44:47]
	v_mfma_f32_16x16x32_bf16 v[36:39], v[156:159], v[188:191], v[36:39]
	v_mfma_f32_16x16x32_bf16 v[36:39], v[160:163], v[192:195], v[36:39]
	v_mfma_f32_16x16x32_bf16 v[28:31], v[164:167], v[188:191], v[28:31]
	v_mfma_f32_16x16x32_bf16 v[28:31], v[176:179], v[192:195], v[28:31]
	v_mfma_f32_16x16x32_bf16 v[20:23], v[156:159], v[196:199], v[20:23]
	v_mfma_f32_16x16x32_bf16 v[20:23], v[160:163], v[200:203], v[20:23]
	v_mfma_f32_16x16x32_bf16 v[12:15], v[164:167], v[196:199], v[12:15]
	v_mfma_f32_16x16x32_bf16 v[12:15], v[176:179], v[200:203], v[12:15]
	v_mfma_f32_16x16x32_bf16 v[4:7], v[156:159], v[204:207], v[4:7]
	v_mfma_f32_16x16x32_bf16 v[4:7], v[160:163], v[208:211], v[4:7]
	v_mfma_f32_16x16x32_bf16 v[0:3], v[164:167], v[204:207], v[0:3]
	v_mfma_f32_16x16x32_bf16 v[0:3], v[176:179], v[208:211], v[0:3]
	s_setprio 0
	s_barrier
	s_add_i32 s31, 0, 0x18000
	s_add_i32 s44, 0, 0x1c000
	v_add_u32_e32 v152, s31, v169
	v_add_u32_e32 v175, s44, v169
	ds_read_b128 v[128:131], v152
	ds_read_b128 v[132:135], v152 offset:1024
	ds_read_b128 v[148:151], v152 offset:2048
	ds_read_b128 v[152:155], v152 offset:3072
	ds_read_b128 v[156:159], v175
	ds_read_b128 v[160:163], v175 offset:1024
	ds_read_b128 v[164:167], v175 offset:2048
	ds_read_b128 v[176:179], v175 offset:3072
	s_add_u32 s42, s42, 0x4000
	s_addc_u32 s43, s43, 0
	s_mov_b32 m0, s19
	v_lshl_add_u64 v[212:213], s[42:43], 0, v[140:141]
	ds_read_b128 v[180:183], v174 offset:32768
	ds_read_b128 v[184:187], v174 offset:33792
	ds_read_b128 v[188:191], v174 offset:34816
	ds_read_b128 v[192:195], v174 offset:35840
	ds_read_b128 v[196:199], v174 offset:36864
	ds_read_b128 v[200:203], v174 offset:37888
	ds_read_b128 v[204:207], v174 offset:38912
	ds_read_b128 v[208:211], v174 offset:39936
	global_load_lds_dwordx4 v[212:213], off
	v_lshl_add_u64 v[212:213], s[42:43], 0, v[138:139]
	s_mov_b32 m0, s20
	s_nop 0
	global_load_lds_dwordx4 v[212:213], off
	s_waitcnt vmcnt(8)
	s_waitcnt lgkmcnt(0)
	s_barrier
	s_setprio 1
	s_waitcnt lgkmcnt(0)
	v_mfma_f32_16x16x32_bf16 v[124:127], v[128:131], v[180:183], v[124:127]
	v_mfma_f32_16x16x32_bf16 v[124:127], v[132:135], v[184:187], v[124:127]
	v_mfma_f32_16x16x32_bf16 v[120:123], v[148:151], v[180:183], v[120:123]
	v_mfma_f32_16x16x32_bf16 v[120:123], v[152:155], v[184:187], v[120:123]
	v_mfma_f32_16x16x32_bf16 v[108:111], v[128:131], v[188:191], v[108:111]
	v_mfma_f32_16x16x32_bf16 v[108:111], v[132:135], v[192:195], v[108:111]
	v_mfma_f32_16x16x32_bf16 v[104:107], v[148:151], v[188:191], v[104:107]
	v_mfma_f32_16x16x32_bf16 v[104:107], v[152:155], v[192:195], v[104:107]
	v_mfma_f32_16x16x32_bf16 v[92:95], v[128:131], v[196:199], v[92:95]
	v_mfma_f32_16x16x32_bf16 v[92:95], v[132:135], v[200:203], v[92:95]
	v_mfma_f32_16x16x32_bf16 v[88:91], v[148:151], v[196:199], v[88:91]
	v_mfma_f32_16x16x32_bf16 v[88:91], v[152:155], v[200:203], v[88:91]
	v_mfma_f32_16x16x32_bf16 v[76:79], v[128:131], v[204:207], v[76:79]
	v_mfma_f32_16x16x32_bf16 v[76:79], v[132:135], v[208:211], v[76:79]
	v_mfma_f32_16x16x32_bf16 v[72:75], v[148:151], v[204:207], v[72:75]
	v_mfma_f32_16x16x32_bf16 v[72:75], v[152:155], v[208:211], v[72:75]
	s_setprio 0
	s_setprio 1
	v_mfma_f32_16x16x32_bf16 v[116:119], v[156:159], v[180:183], v[116:119]
	v_mfma_f32_16x16x32_bf16 v[116:119], v[160:163], v[184:187], v[116:119]
	v_mfma_f32_16x16x32_bf16 v[112:115], v[164:167], v[180:183], v[112:115]
	v_mfma_f32_16x16x32_bf16 v[112:115], v[176:179], v[184:187], v[112:115]
	v_mfma_f32_16x16x32_bf16 v[100:103], v[156:159], v[188:191], v[100:103]
	v_mfma_f32_16x16x32_bf16 v[100:103], v[160:163], v[192:195], v[100:103]
	v_mfma_f32_16x16x32_bf16 v[96:99], v[164:167], v[188:191], v[96:99]
	v_mfma_f32_16x16x32_bf16 v[96:99], v[176:179], v[192:195], v[96:99]
	v_mfma_f32_16x16x32_bf16 v[84:87], v[156:159], v[196:199], v[84:87]
	v_mfma_f32_16x16x32_bf16 v[84:87], v[160:163], v[200:203], v[84:87]
	v_mfma_f32_16x16x32_bf16 v[80:83], v[164:167], v[196:199], v[80:83]
	v_mfma_f32_16x16x32_bf16 v[80:83], v[176:179], v[200:203], v[80:83]
	v_mfma_f32_16x16x32_bf16 v[68:71], v[156:159], v[204:207], v[68:71]
	v_mfma_f32_16x16x32_bf16 v[68:71], v[160:163], v[208:211], v[68:71]
	v_mfma_f32_16x16x32_bf16 v[64:67], v[164:167], v[204:207], v[64:67]
	v_mfma_f32_16x16x32_bf16 v[64:67], v[176:179], v[208:211], v[64:67]
	s_setprio 0
	s_barrier
; #define PG8_STAGE(bufoff, gbase, voff) do { _Pragma("unroll") for (int _i = 0; _i < 2; ++_i) \
;         __builtin_amdgcn_global_load_lds((const unsigned*)((const char*)(gbase) + (voff)[_i]), (PG8_LAS unsigned*)(lds + (bufoff) + ldsw + _i * 8192), 16, 0, 0); } while (0)
; #define PG8_LDA(dst, b, h) do { _Pragma("unroll") for (int m = 0; m < 4; ++m) _Pragma("unroll") for (int k = 0; k < 2; ++k) dst[m][k] = *(const PG8_LAS bf16x8*)(lds + PG8_SA(b, h) + aoff + m * 2048 + k * 1024); } while (0)
; #define PG8_MMA(ai, bj, At, Bt) do { __builtin_amdgcn_s_setprio(1); _Pragma("unroll") for (int m = 0; m < 4; ++m) _Pragma("unroll") for (int n = 0; n < 2; ++n) _Pragma("unroll") for (int k = 0; k < 2; ++k) \
;         acc[ai][bj][m][n] = __builtin_amdgcn_mfma_f32_16x16x32_bf16(Bt[n][k], At[m][k], acc[ai][bj][m][n], 0, 0, 0); __builtin_amdgcn_s_setprio(0); } while (0)
; #define PG8_WAIT_V(n) asm volatile("s_waitcnt vmcnt(" #n ")" ::: "memory")
; #define PG8_WAIT_L(n) asm volatile("s_waitcnt lgkmcnt(" #n ")" ::: "memory")
; #define PG8_BAR __builtin_amdgcn_s_barrier()
; #define PG8_SCHED __builtin_amdgcn_sched_barrier(0)
; template <class Epi, class Sched, bool ALIGN_EPI = false, bool SP2 = false>
; __device__ __forceinline__ void gemm_phase(PG8_LAS unsigned char* lds, const Gemm g, const Sched& S, const Epi& E) {
;     ...
;             PG8_LDA(At, 1, 1); PG8_STAGE(PG8_SB(1, 0), b3, voffB); PG8_STAGE(PG8_SB(1, 1), b3 + hstepB, voffB); PG8_STAGE(PG8_SA(1, 0), a3, voffA);
;             PG8_WAIT_V(8); PG8_WAIT_L(0); PG8_BAR; PG8_MMA(1, 0, At, B0); PG8_MMA(1, 1, At, B1); PG8_BAR; PG8_SCHED;
	s_add_u32 s42, s40, 0x8000
	s_addc_u32 s43, s41, 0
	s_add_i32 s31, s31, s14
	v_lshl_add_u64 v[212:213], s[42:43], 0, v[220:221]
	s_mov_b32 m0, s31
	ds_read_b128 v[180:183], v174 offset:49152
	ds_read_b128 v[184:187], v174 offset:50176
	ds_read_b128 v[188:191], v174 offset:51200
	ds_read_b128 v[192:195], v174 offset:52224
	ds_read_b128 v[196:199], v174 offset:53248
	ds_read_b128 v[200:203], v174 offset:54272
	ds_read_b128 v[204:207], v174 offset:55296
	ds_read_b128 v[208:211], v174 offset:56320
	global_load_lds_dwordx4 v[212:213], off
	s_add_i32 m0, s31, 0x2000
	s_add_u32 s40, s40, 0xc000
	v_lshl_add_u64 v[212:213], s[42:43], 0, v[136:137]
	s_addc_u32 s41, s41, 0
	s_add_i32 s31, s44, s14
	global_load_lds_dwordx4 v[212:213], off
	v_lshl_add_u64 v[212:213], s[40:41], 0, v[220:221]
	s_mov_b32 m0, s31
	s_nop 0
	global_load_lds_dwordx4 v[212:213], off
	v_lshl_add_u64 v[212:213], s[40:41], 0, v[136:137]
	s_add_i32 m0, s31, 0x2000
	s_nop 0
	global_load_lds_dwordx4 v[212:213], off
	v_lshl_add_u64 v[212:213], s[38:39], 0, v[140:141]
	s_mov_b32 m0, s21
	s_nop 0
	global_load_lds_dwordx4 v[212:213], off
	v_lshl_add_u64 v[212:213], s[38:39], 0, v[138:139]
	s_mov_b32 m0, s22
	s_nop 0
	global_load_lds_dwordx4 v[212:213], off
	s_waitcnt vmcnt(8)
	s_waitcnt lgkmcnt(0)
	s_barrier
	s_setprio 1
	s_waitcnt lgkmcnt(0)
	v_mfma_f32_16x16x32_bf16 v[60:63], v[128:131], v[180:183], v[60:63]
	v_mfma_f32_16x16x32_bf16 v[60:63], v[132:135], v[184:187], v[60:63]
	v_mfma_f32_16x16x32_bf16 v[56:59], v[148:151], v[180:183], v[56:59]
	v_mfma_f32_16x16x32_bf16 v[56:59], v[152:155], v[184:187], v[56:59]
	v_mfma_f32_16x16x32_bf16 v[48:51], v[128:131], v[188:191], v[48:51]
	v_mfma_f32_16x16x32_bf16 v[48:51], v[132:135], v[192:195], v[48:51]
	v_mfma_f32_16x16x32_bf16 v[40:43], v[148:151], v[188:191], v[40:43]
	v_mfma_f32_16x16x32_bf16 v[40:43], v[152:155], v[192:195], v[40:43]
	v_mfma_f32_16x16x32_bf16 v[32:35], v[128:131], v[196:199], v[32:35]
	v_mfma_f32_16x16x32_bf16 v[32:35], v[132:135], v[200:203], v[32:35]
	v_mfma_f32_16x16x32_bf16 v[24:27], v[148:151], v[196:199], v[24:27]
	v_mfma_f32_16x16x32_bf16 v[24:27], v[152:155], v[200:203], v[24:27]
	v_mfma_f32_16x16x32_bf16 v[16:19], v[128:131], v[204:207], v[16:19]
	v_mfma_f32_16x16x32_bf16 v[16:19], v[132:135], v[208:211], v[16:19]
	v_mfma_f32_16x16x32_bf16 v[8:11], v[148:151], v[204:207], v[8:11]
	v_mfma_f32_16x16x32_bf16 v[8:11], v[152:155], v[208:211], v[8:11]
	s_setprio 0
	s_setprio 1
	v_mfma_f32_16x16x32_bf16 v[52:55], v[156:159], v[180:183], v[52:55]
	v_mfma_f32_16x16x32_bf16 v[52:55], v[160:163], v[184:187], v[52:55]
	v_mfma_f32_16x16x32_bf16 v[44:47], v[164:167], v[180:183], v[44:47]
	v_mfma_f32_16x16x32_bf16 v[44:47], v[176:179], v[184:187], v[44:47]
	v_mfma_f32_16x16x32_bf16 v[36:39], v[156:159], v[188:191], v[36:39]
	v_mfma_f32_16x16x32_bf16 v[36:39], v[160:163], v[192:195], v[36:39]
	v_mfma_f32_16x16x32_bf16 v[28:31], v[164:167], v[188:191], v[28:31]
	v_mfma_f32_16x16x32_bf16 v[28:31], v[176:179], v[192:195], v[28:31]
	v_mfma_f32_16x16x32_bf16 v[20:23], v[156:159], v[196:199], v[20:23]
	v_mfma_f32_16x16x32_bf16 v[20:23], v[160:163], v[200:203], v[20:23]
	v_mfma_f32_16x16x32_bf16 v[12:15], v[164:167], v[196:199], v[12:15]
	v_mfma_f32_16x16x32_bf16 v[12:15], v[176:179], v[200:203], v[12:15]
	v_mfma_f32_16x16x32_bf16 v[4:7], v[156:159], v[204:207], v[4:7]
	v_mfma_f32_16x16x32_bf16 v[4:7], v[160:163], v[208:211], v[4:7]
	v_mfma_f32_16x16x32_bf16 v[0:3], v[164:167], v[204:207], v[0:3]
	v_mfma_f32_16x16x32_bf16 v[0:3], v[176:179], v[208:211], v[0:3]
	s_setprio 0
	s_barrier
	s_add_i32 s30, s30, 2
	s_add_u32 s36, s36, 0x10000
	s_addc_u32 s37, s37, 0
	s_add_u32 s28, s28, 0x10000
	s_addc_u32 s29, s29, 0
	s_cmp_gt_u32 s30, 29
	s_cbranch_scc0 .LBB0_232
	s_and_b64 vcc, exec, s[8:9]
	s_cbranch_vccz .LBB0_235
	s_barrier

; #define PG8_STAGE(bufoff, gbase, voff) do { _Pragma("unroll") for (int _i = 0; _i < 2; ++_i) \
;         __builtin_amdgcn_global_load_lds((const unsigned*)((const char*)(gbase) + (voff)[_i]), (PG8_LAS unsigned*)(lds + (bufoff) + ldsw + _i * 8192), 16, 0, 0); } while (0)
; #define PG8_LDA(dst, b, h) do { _Pragma("unroll") for (int m = 0; m < 4; ++m) _Pragma("unroll") for (int k = 0; k < 2; ++k) dst[m][k] = *(const PG8_LAS bf16x8*)(lds + PG8_SA(b, h) + aoff + m * 2048 + k * 1024); } while (0)
; #define PG8_LDB(dst, b, h) do { _Pragma("unroll") for (int n = 0; n < 2; ++n) _Pragma("unroll") for (int k = 0; k < 2; ++k) dst[n][k] = *(const PG8_LAS bf16x8*)(lds + PG8_SB(b, h) + boff + n * 2048 + k * 1024); } while (0)
; #define PG8_WAIT_V(n) asm volatile("s_waitcnt vmcnt(" #n ")" ::: "memory")
; #define PG8_WAIT_L(n) asm volatile("s_waitcnt lgkmcnt(" #n ")" ::: "memory")
; #define PG8_BAR __builtin_amdgcn_s_barrier()
; #define PG8_SCHED __builtin_amdgcn_sched_barrier(0)
; template <class Epi, class Sched, bool ALIGN_EPI = false, bool SP2 = false>
; __device__ __forceinline__ void gemm_phase(PG8_LAS unsigned char* lds, const Gemm g, const Sched& S, const Epi& E) {
;     ...
;         const bool has_next = S.next(ui + 1, nxt);
;         const char* nA = has_next ? (const char*)g.A + (size_t)nxt.pm * tstep : cA; const char* nB = has_next ? (const char*)g.Bt + (size_t)nxt.pn * tstep : cB;
;         for (int t = 0; t < nt; t += 2) {
;             const bool last = (t == nt - 2);
;             const char* a1 = cA + (size_t)(t + 1) * kstepB;
;             const char* a2 = last ? nA : cA + (size_t)(t + 2) * kstepB; const char* b2 = last ? nB : cB + (size_t)(t + 2) * kstepB;
;             const char* a3 = a2 + kstepB; const char* b3 = b2 + kstepB;
;             if (last && has_next) S.a_ready(nxt);
;             if constexpr (SP2) {
;             PG8_LDB(B0, 0, 0); PG8_LDB(B1, 0, 1); PG8_SCHED; PG8_LDA(At, 0, 0); PG8_STAGE(PG8_SA(1, 1), a1 + hstepB, voffA);
;             PG8_WAIT_V(8); PG8_WAIT_L(0); PG8_BAR; PG8_MMA(0, 0, At, B0); PG8_MMA(0, 1, At, B1); PG8_BAR; PG8_SCHED;
;             PG8_LDA(At, 0, 1); PG8_STAGE(PG8_SB(0, 0), b2, voffB); PG8_STAGE(PG8_SB(0, 1), b2 + hstepB, voffB); PG8_STAGE(PG8_SA(0, 0), a2, voffA);
;             PG8_WAIT_V(8); PG8_WAIT_L(0); PG8_BAR; PG8_MMA(1, 0, At, B0); PG8_MMA(1, 1, At, B1); PG8_BAR; PG8_SCHED;
.LBB0_263:
	s_add_u32 s38, s36, 0x4000
	s_addc_u32 s39, s37, 0
	s_cmp_eq_u32 s62, 28
	s_cselect_b32 s42, s30, s38
	s_cselect_b32 s43, s13, s39
	s_cselect_b32 s40, s31, s44
	s_cselect_b32 s41, s11, s45
	s_add_u32 s38, s42, 0x8000
	s_addc_u32 s39, s43, 0
	s_add_i32 s63, 0, 0x10000
	v_add_u32_e32 v151, s63, v165
	s_add_i32 s75, 0, 0x14000
	ds_read_b128 v[128:131], v151
	ds_read_b128 v[132:135], v151 offset:1024
	ds_read_b128 v[152:155], v151 offset:2048
	ds_read_b128 v[156:159], v151 offset:3072
	v_add_u32_e32 v151, s75, v165
	ds_read_b128 v[160:163], v151
	ds_read_b128 v[170:173], v151 offset:1024
	ds_read_b128 v[174:177], v151 offset:2048
	ds_read_b128 v[178:181], v151 offset:3072
	v_lshl_add_u64 v[214:215], s[36:37], 0, v[146:147]
	s_add_i32 m0, s19, 0xc000
	ds_read_b128 v[182:185], v168
	ds_read_b128 v[186:189], v168 offset:1024
	ds_read_b128 v[190:193], v168 offset:2048
	ds_read_b128 v[194:197], v168 offset:3072
	ds_read_b128 v[198:201], v168 offset:4096
	ds_read_b128 v[202:205], v168 offset:5120
	ds_read_b128 v[206:209], v168 offset:6144
	ds_read_b128 v[210:213], v168 offset:7168
	global_load_lds_dwordx4 v[214:215], off
	v_lshl_add_u64 v[214:215], s[36:37], 0, v[148:149]
	s_add_i32 m0, s19, 0xe000
	s_nop 0
	global_load_lds_dwordx4 v[214:215], off
	s_waitcnt vmcnt(8)
	s_waitcnt lgkmcnt(0)
	s_barrier
	s_setprio 1
	s_waitcnt lgkmcnt(0)
	v_mfma_f32_16x16x32_bf16 v[124:127], v[128:131], v[182:185], v[124:127]
	v_mfma_f32_16x16x32_bf16 v[124:127], v[132:135], v[186:189], v[124:127]
	v_mfma_f32_16x16x32_bf16 v[116:119], v[152:155], v[182:185], v[116:119]
	v_mfma_f32_16x16x32_bf16 v[116:119], v[156:159], v[186:189], v[116:119]
	v_mfma_f32_16x16x32_bf16 v[108:111], v[128:131], v[190:193], v[108:111]
	v_mfma_f32_16x16x32_bf16 v[108:111], v[132:135], v[194:197], v[108:111]
	v_mfma_f32_16x16x32_bf16 v[100:103], v[152:155], v[190:193], v[100:103]
	v_mfma_f32_16x16x32_bf16 v[100:103], v[156:159], v[194:197], v[100:103]
	v_mfma_f32_16x16x32_bf16 v[92:95], v[128:131], v[198:201], v[92:95]
	v_mfma_f32_16x16x32_bf16 v[92:95], v[132:135], v[202:205], v[92:95]
	v_mfma_f32_16x16x32_bf16 v[84:87], v[152:155], v[198:201], v[84:87]
	v_mfma_f32_16x16x32_bf16 v[84:87], v[156:159], v[202:205], v[84:87]
	v_mfma_f32_16x16x32_bf16 v[76:79], v[128:131], v[206:209], v[76:79]
	v_mfma_f32_16x16x32_bf16 v[76:79], v[132:135], v[210:213], v[76:79]
	v_mfma_f32_16x16x32_bf16 v[68:71], v[152:155], v[206:209], v[68:71]
	v_mfma_f32_16x16x32_bf16 v[68:71], v[156:159], v[210:213], v[68:71]
	s_setprio 0
	s_setprio 1
	v_mfma_f32_16x16x32_bf16 v[120:123], v[160:163], v[182:185], v[120:123]
	v_mfma_f32_16x16x32_bf16 v[120:123], v[170:173], v[186:189], v[120:123]
	v_mfma_f32_16x16x32_bf16 v[112:115], v[174:177], v[182:185], v[112:115]
	v_mfma_f32_16x16x32_bf16 v[112:115], v[178:181], v[186:189], v[112:115]
	v_mfma_f32_16x16x32_bf16 v[104:107], v[160:163], v[190:193], v[104:107]
	v_mfma_f32_16x16x32_bf16 v[104:107], v[170:173], v[194:197], v[104:107]
	v_mfma_f32_16x16x32_bf16 v[96:99], v[174:177], v[190:193], v[96:99]
	v_mfma_f32_16x16x32_bf16 v[96:99], v[178:181], v[194:197], v[96:99]
	v_mfma_f32_16x16x32_bf16 v[88:91], v[160:163], v[198:201], v[88:91]
	v_mfma_f32_16x16x32_bf16 v[88:91], v[170:173], v[202:205], v[88:91]
	v_mfma_f32_16x16x32_bf16 v[80:83], v[174:177], v[198:201], v[80:83]
	v_mfma_f32_16x16x32_bf16 v[80:83], v[178:181], v[202:205], v[80:83]
	v_mfma_f32_16x16x32_bf16 v[72:75], v[160:163], v[206:209], v[72:75]
	v_mfma_f32_16x16x32_bf16 v[72:75], v[170:173], v[210:213], v[72:75]
	v_mfma_f32_16x16x32_bf16 v[64:67], v[174:177], v[206:209], v[64:67]
	v_mfma_f32_16x16x32_bf16 v[64:67], v[178:181], v[210:213], v[64:67]
	s_setprio 0
	s_barrier
	s_add_i32 s63, s63, s16
	v_lshl_add_u64 v[214:215], s[40:41], 0, v[140:141]
	s_mov_b32 m0, s63
	ds_read_b128 v[182:185], v168 offset:16384
	ds_read_b128 v[186:189], v168 offset:17408
	ds_read_b128 v[190:193], v168 offset:18432
	ds_read_b128 v[194:197], v168 offset:19456
	ds_read_b128 v[198:201], v168 offset:20480
	ds_read_b128 v[202:205], v168 offset:21504
	ds_read_b128 v[206:209], v168 offset:22528
	ds_read_b128 v[210:213], v168 offset:23552
	global_load_lds_dwordx4 v[214:215], off
	s_add_i32 m0, s63, 0x2000
	s_add_u32 s66, s40, 0x4000
	v_lshl_add_u64 v[214:215], s[40:41], 0, v[136:137]
	s_addc_u32 s67, s41, 0
	s_add_i32 s63, s75, s16
	global_load_lds_dwordx4 v[214:215], off
	v_lshl_add_u64 v[214:215], s[66:67], 0, v[140:141]
	s_mov_b32 m0, s63
	s_nop 0
	global_load_lds_dwordx4 v[214:215], off
	v_lshl_add_u64 v[214:215], s[66:67], 0, v[136:137]
	s_add_i32 m0, s63, 0x2000
	s_nop 0
	global_load_lds_dwordx4 v[214:215], off
	v_lshl_add_u64 v[214:215], s[42:43], 0, v[142:143]
	s_mov_b32 m0, s19
	s_nop 0
	global_load_lds_dwordx4 v[214:215], off
	v_lshl_add_u64 v[214:215], s[42:43], 0, v[138:139]
	s_mov_b32 m0, s20
	s_nop 0
	global_load_lds_dwordx4 v[214:215], off
	s_waitcnt vmcnt(8)
	s_waitcnt lgkmcnt(0)
	s_barrier
; #define PG8_STAGE(bufoff, gbase, voff) do { _Pragma("unroll") for (int _i = 0; _i < 2; ++_i) \
;         __builtin_amdgcn_global_load_lds((const unsigned*)((const char*)(gbase) + (voff)[_i]), (PG8_LAS unsigned*)(lds + (bufoff) + ldsw + _i * 8192), 16, 0, 0); } while (0)
; #define PG8_LDA(dst, b, h) do { _Pragma("unroll") for (int m = 0; m < 4; ++m) _Pragma("unroll") for (int k = 0; k < 2; ++k) dst[m][k] = *(const PG8_LAS bf16x8*)(lds + PG8_SA(b, h) + aoff + m * 2048 + k * 1024); } while (0)
; #define PG8_LDB(dst, b, h) do { _Pragma("unroll") for (int n = 0; n < 2; ++n) _Pragma("unroll") for (int k = 0; k < 2; ++k) dst[n][k] = *(const PG8_LAS bf16x8*)(lds + PG8_SB(b, h) + boff + n * 2048 + k * 1024); } while (0)
; #define PG8_MMA(ai, bj, At, Bt) do { __builtin_amdgcn_s_setprio(1); _Pragma("unroll") for (int m = 0; m < 4; ++m) _Pragma("unroll") for (int n = 0; n < 2; ++n) _Pragma("unroll") for (int k = 0; k < 2; ++k) \
;         acc[ai][bj][m][n] = __builtin_amdgcn_mfma_f32_16x16x32_bf16(Bt[n][k], At[m][k], acc[ai][bj][m][n], 0, 0, 0); __builtin_amdgcn_s_setprio(0); } while (0)
; #define PG8_WAIT_V(n) asm volatile("s_waitcnt vmcnt(" #n ")" ::: "memory")
; #define PG8_WAIT_L(n) asm volatile("s_waitcnt lgkmcnt(" #n ")" ::: "memory")
; #define PG8_BAR __builtin_amdgcn_s_barrier()
; #define PG8_SCHED __builtin_amdgcn_sched_barrier(0)
; template <class Epi, class Sched, bool ALIGN_EPI = false, bool SP2 = false>
; __device__ __forceinline__ void gemm_phase(PG8_LAS unsigned char* lds, const Gemm g, const Sched& S, const Epi& E) {
;     ...
;             PG8_WAIT_V(8); PG8_WAIT_L(0); PG8_BAR; PG8_MMA(1, 0, At, B0); PG8_MMA(1, 1, At, B1); PG8_BAR; PG8_SCHED;
;             PG8_LDB(B0, 1, 0); PG8_LDB(B1, 1, 1); PG8_SCHED; PG8_LDA(At, 1, 0); PG8_STAGE(PG8_SA(0, 1), a2 + hstepB, voffA);
;             PG8_WAIT_V(8); PG8_WAIT_L(0); PG8_BAR; PG8_MMA(0, 0, At, B0); PG8_MMA(0, 1, At, B1); PG8_BAR; PG8_SCHED;
	s_setprio 1
	s_waitcnt lgkmcnt(0)
	v_mfma_f32_16x16x32_bf16 v[60:63], v[128:131], v[182:185], v[60:63]
	v_mfma_f32_16x16x32_bf16 v[60:63], v[132:135], v[186:189], v[60:63]
	v_mfma_f32_16x16x32_bf16 v[52:55], v[152:155], v[182:185], v[52:55]
	v_mfma_f32_16x16x32_bf16 v[52:55], v[156:159], v[186:189], v[52:55]
	v_mfma_f32_16x16x32_bf16 v[44:47], v[128:131], v[190:193], v[44:47]
	v_mfma_f32_16x16x32_bf16 v[44:47], v[132:135], v[194:197], v[44:47]
	v_mfma_f32_16x16x32_bf16 v[36:39], v[152:155], v[190:193], v[36:39]
	v_mfma_f32_16x16x32_bf16 v[36:39], v[156:159], v[194:197], v[36:39]
	v_mfma_f32_16x16x32_bf16 v[28:31], v[128:131], v[198:201], v[28:31]
	v_mfma_f32_16x16x32_bf16 v[28:31], v[132:135], v[202:205], v[28:31]
	v_mfma_f32_16x16x32_bf16 v[20:23], v[152:155], v[198:201], v[20:23]
	v_mfma_f32_16x16x32_bf16 v[20:23], v[156:159], v[202:205], v[20:23]
	v_mfma_f32_16x16x32_bf16 v[12:15], v[128:131], v[206:209], v[12:15]
	v_mfma_f32_16x16x32_bf16 v[12:15], v[132:135], v[210:213], v[12:15]
	v_mfma_f32_16x16x32_bf16 v[4:7], v[152:155], v[206:209], v[4:7]
	v_mfma_f32_16x16x32_bf16 v[4:7], v[156:159], v[210:213], v[4:7]
	s_setprio 0
	s_setprio 1
	v_mfma_f32_16x16x32_bf16 v[56:59], v[160:163], v[182:185], v[56:59]
	v_mfma_f32_16x16x32_bf16 v[56:59], v[170:173], v[186:189], v[56:59]
	v_mfma_f32_16x16x32_bf16 v[48:51], v[174:177], v[182:185], v[48:51]
	v_mfma_f32_16x16x32_bf16 v[48:51], v[178:181], v[186:189], v[48:51]
	v_mfma_f32_16x16x32_bf16 v[40:43], v[160:163], v[190:193], v[40:43]
	v_mfma_f32_16x16x32_bf16 v[40:43], v[170:173], v[194:197], v[40:43]
	v_mfma_f32_16x16x32_bf16 v[32:35], v[174:177], v[190:193], v[32:35]
	v_mfma_f32_16x16x32_bf16 v[32:35], v[178:181], v[194:197], v[32:35]
	v_mfma_f32_16x16x32_bf16 v[24:27], v[160:163], v[198:201], v[24:27]
	v_mfma_f32_16x16x32_bf16 v[24:27], v[170:173], v[202:205], v[24:27]
	v_mfma_f32_16x16x32_bf16 v[16:19], v[174:177], v[198:201], v[16:19]
	v_mfma_f32_16x16x32_bf16 v[16:19], v[178:181], v[202:205], v[16:19]
	v_mfma_f32_16x16x32_bf16 v[8:11], v[160:163], v[206:209], v[8:11]
	v_mfma_f32_16x16x32_bf16 v[8:11], v[170:173], v[210:213], v[8:11]
	v_mfma_f32_16x16x32_bf16 v[0:3], v[174:177], v[206:209], v[0:3]
	v_mfma_f32_16x16x32_bf16 v[0:3], v[178:181], v[210:213], v[0:3]
	s_setprio 0
	s_barrier
	s_add_i32 s63, 0, 0x18000
	v_add_u32_e32 v151, s63, v165
	s_add_i32 s66, 0, 0x1c000
	ds_read_b128 v[128:131], v151
	ds_read_b128 v[132:135], v151 offset:1024
	ds_read_b128 v[152:155], v151 offset:2048
	ds_read_b128 v[156:159], v151 offset:3072
	v_add_u32_e32 v151, s66, v165
	ds_read_b128 v[160:163], v151
	ds_read_b128 v[170:173], v151 offset:1024
	ds_read_b128 v[174:177], v151 offset:2048
	ds_read_b128 v[178:181], v151 offset:3072
	s_add_u32 s42, s42, 0x4000
	s_addc_u32 s43, s43, 0
	s_mov_b32 m0, s21
	v_lshl_add_u64 v[214:215], s[42:43], 0, v[142:143]
	ds_read_b128 v[182:185], v168 offset:32768
	ds_read_b128 v[186:189], v168 offset:33792
	ds_read_b128 v[190:193], v168 offset:34816
	ds_read_b128 v[194:197], v168 offset:35840
	ds_read_b128 v[198:201], v168 offset:36864
	ds_read_b128 v[202:205], v168 offset:37888
	ds_read_b128 v[206:209], v168 offset:38912
	ds_read_b128 v[210:213], v168 offset:39936
	global_load_lds_dwordx4 v[214:215], off
	v_lshl_add_u64 v[214:215], s[42:43], 0, v[138:139]
	s_mov_b32 m0, s22
	s_nop 0
	global_load_lds_dwordx4 v[214:215], off
	s_waitcnt vmcnt(8)
	s_waitcnt lgkmcnt(0)
	s_barrier
	s_setprio 1
	s_waitcnt lgkmcnt(0)
	v_mfma_f32_16x16x32_bf16 v[124:127], v[128:131], v[182:185], v[124:127]
	v_mfma_f32_16x16x32_bf16 v[124:127], v[132:135], v[186:189], v[124:127]
	v_mfma_f32_16x16x32_bf16 v[116:119], v[152:155], v[182:185], v[116:119]
	v_mfma_f32_16x16x32_bf16 v[116:119], v[156:159], v[186:189], v[116:119]
	v_mfma_f32_16x16x32_bf16 v[108:111], v[128:131], v[190:193], v[108:111]
	v_mfma_f32_16x16x32_bf16 v[108:111], v[132:135], v[194:197], v[108:111]
	v_mfma_f32_16x16x32_bf16 v[100:103], v[152:155], v[190:193], v[100:103]
	v_mfma_f32_16x16x32_bf16 v[100:103], v[156:159], v[194:197], v[100:103]
	v_mfma_f32_16x16x32_bf16 v[92:95], v[128:131], v[198:201], v[92:95]
	v_mfma_f32_16x16x32_bf16 v[92:95], v[132:135], v[202:205], v[92:95]
	v_mfma_f32_16x16x32_bf16 v[84:87], v[152:155], v[198:201], v[84:87]
	v_mfma_f32_16x16x32_bf16 v[84:87], v[156:159], v[202:205], v[84:87]
	v_mfma_f32_16x16x32_bf16 v[76:79], v[128:131], v[206:209], v[76:79]
	v_mfma_f32_16x16x32_bf16 v[76:79], v[132:135], v[210:213], v[76:79]
	v_mfma_f32_16x16x32_bf16 v[68:71], v[152:155], v[206:209], v[68:71]
	v_mfma_f32_16x16x32_bf16 v[68:71], v[156:159], v[210:213], v[68:71]
	s_setprio 0
	s_setprio 1
	v_mfma_f32_16x16x32_bf16 v[120:123], v[160:163], v[182:185], v[120:123]
	v_mfma_f32_16x16x32_bf16 v[120:123], v[170:173], v[186:189], v[120:123]
	v_mfma_f32_16x16x32_bf16 v[112:115], v[174:177], v[182:185], v[112:115]
	v_mfma_f32_16x16x32_bf16 v[112:115], v[178:181], v[186:189], v[112:115]
	v_mfma_f32_16x16x32_bf16 v[104:107], v[160:163], v[190:193], v[104:107]
	v_mfma_f32_16x16x32_bf16 v[104:107], v[170:173], v[194:197], v[104:107]
	v_mfma_f32_16x16x32_bf16 v[96:99], v[174:177], v[190:193], v[96:99]
	v_mfma_f32_16x16x32_bf16 v[96:99], v[178:181], v[194:197], v[96:99]
	v_mfma_f32_16x16x32_bf16 v[88:91], v[160:163], v[198:201], v[88:91]
	v_mfma_f32_16x16x32_bf16 v[88:91], v[170:173], v[202:205], v[88:91]
	v_mfma_f32_16x16x32_bf16 v[80:83], v[174:177], v[198:201], v[80:83]
	v_mfma_f32_16x16x32_bf16 v[80:83], v[178:181], v[202:205], v[80:83]
	v_mfma_f32_16x16x32_bf16 v[72:75], v[160:163], v[206:209], v[72:75]
	v_mfma_f32_16x16x32_bf16 v[72:75], v[170:173], v[210:213], v[72:75]
	v_mfma_f32_16x16x32_bf16 v[64:67], v[174:177], v[206:209], v[64:67]
	v_mfma_f32_16x16x32_bf16 v[64:67], v[178:181], v[210:213], v[64:67]
	s_setprio 0
	s_barrier
; #define PG8_STAGE(bufoff, gbase, voff) do { _Pragma("unroll") for (int _i = 0; _i < 2; ++_i) \
;         __builtin_amdgcn_global_load_lds((const unsigned*)((const char*)(gbase) + (voff)[_i]), (PG8_LAS unsigned*)(lds + (bufoff) + ldsw + _i * 8192), 16, 0, 0); } while (0)
; #define PG8_LDA(dst, b, h) do { _Pragma("unroll") for (int m = 0; m < 4; ++m) _Pragma("unroll") for (int k = 0; k < 2; ++k) dst[m][k] = *(const PG8_LAS bf16x8*)(lds + PG8_SA(b, h) + aoff + m * 2048 + k * 1024); } while (0)
; #define PG8_MMA(ai, bj, At, Bt) do { __builtin_amdgcn_s_setprio(1); _Pragma("unroll") for (int m = 0; m < 4; ++m) _Pragma("unroll") for (int n = 0; n < 2; ++n) _Pragma("unroll") for (int k = 0; k < 2; ++k) \
;         acc[ai][bj][m][n] = __builtin_amdgcn_mfma_f32_16x16x32_bf16(Bt[n][k], At[m][k], acc[ai][bj][m][n], 0, 0, 0); __builtin_amdgcn_s_setprio(0); } while (0)
; #define PG8_WAIT_V(n) asm volatile("s_waitcnt vmcnt(" #n ")" ::: "memory")
; #define PG8_WAIT_L(n) asm volatile("s_waitcnt lgkmcnt(" #n ")" ::: "memory")
; #define PG8_BAR __builtin_amdgcn_s_barrier()
; #define PG8_SCHED __builtin_amdgcn_sched_barrier(0)
; template <class Epi, class Sched, bool ALIGN_EPI = false, bool SP2 = false>
; __device__ __forceinline__ void gemm_phase(PG8_LAS unsigned char* lds, const Gemm g, const Sched& S, const Epi& E) {
;     ...
;         for (int t = 0; t < nt; t += 2) {
;     ...
;             PG8_LDA(At, 1, 1); PG8_STAGE(PG8_SB(1, 0), b3, voffB); PG8_STAGE(PG8_SB(1, 1), b3 + hstepB, voffB); PG8_STAGE(PG8_SA(1, 0), a3, voffA);
;             PG8_WAIT_V(8); PG8_WAIT_L(0); PG8_BAR; PG8_MMA(1, 0, At, B0); PG8_MMA(1, 1, At, B1); PG8_BAR; PG8_SCHED;
	s_add_u32 s42, s40, 0x8000
	s_addc_u32 s43, s41, 0
	s_add_i32 s63, s63, s16
	v_lshl_add_u64 v[214:215], s[42:43], 0, v[140:141]
	s_mov_b32 m0, s63
	ds_read_b128 v[182:185], v168 offset:49152
	ds_read_b128 v[186:189], v168 offset:50176
	ds_read_b128 v[190:193], v168 offset:51200
	ds_read_b128 v[194:197], v168 offset:52224
	ds_read_b128 v[198:201], v168 offset:53248
	ds_read_b128 v[202:205], v168 offset:54272
	ds_read_b128 v[206:209], v168 offset:55296
	ds_read_b128 v[210:213], v168 offset:56320
	global_load_lds_dwordx4 v[214:215], off
	s_add_i32 m0, s63, 0x2000
	s_add_u32 s40, s40, 0xc000
	v_lshl_add_u64 v[214:215], s[42:43], 0, v[136:137]
	s_addc_u32 s41, s41, 0
	s_add_i32 s42, s66, s16
	global_load_lds_dwordx4 v[214:215], off
	v_lshl_add_u64 v[214:215], s[40:41], 0, v[140:141]
	s_mov_b32 m0, s42
	s_nop 0
	global_load_lds_dwordx4 v[214:215], off
	v_lshl_add_u64 v[214:215], s[40:41], 0, v[136:137]
	s_add_i32 m0, s42, 0x2000
	s_nop 0
	global_load_lds_dwordx4 v[214:215], off
	v_lshl_add_u64 v[214:215], s[38:39], 0, v[142:143]
	s_mov_b32 m0, s25
	s_nop 0
	global_load_lds_dwordx4 v[214:215], off
	v_lshl_add_u64 v[214:215], s[38:39], 0, v[138:139]
	s_mov_b32 m0, s26
	s_nop 0
	global_load_lds_dwordx4 v[214:215], off
	s_waitcnt vmcnt(8)
	s_waitcnt lgkmcnt(0)
	s_barrier
	s_setprio 1
	s_waitcnt lgkmcnt(0)
	v_mfma_f32_16x16x32_bf16 v[60:63], v[128:131], v[182:185], v[60:63]
	v_mfma_f32_16x16x32_bf16 v[60:63], v[132:135], v[186:189], v[60:63]
	v_mfma_f32_16x16x32_bf16 v[52:55], v[152:155], v[182:185], v[52:55]
	v_mfma_f32_16x16x32_bf16 v[52:55], v[156:159], v[186:189], v[52:55]
	v_mfma_f32_16x16x32_bf16 v[44:47], v[128:131], v[190:193], v[44:47]
	v_mfma_f32_16x16x32_bf16 v[44:47], v[132:135], v[194:197], v[44:47]
	v_mfma_f32_16x16x32_bf16 v[36:39], v[152:155], v[190:193], v[36:39]
	v_mfma_f32_16x16x32_bf16 v[36:39], v[156:159], v[194:197], v[36:39]
	v_mfma_f32_16x16x32_bf16 v[28:31], v[128:131], v[198:201], v[28:31]
	v_mfma_f32_16x16x32_bf16 v[28:31], v[132:135], v[202:205], v[28:31]
	v_mfma_f32_16x16x32_bf16 v[20:23], v[152:155], v[198:201], v[20:23]
	v_mfma_f32_16x16x32_bf16 v[20:23], v[156:159], v[202:205], v[20:23]
	v_mfma_f32_16x16x32_bf16 v[12:15], v[128:131], v[206:209], v[12:15]
	v_mfma_f32_16x16x32_bf16 v[12:15], v[132:135], v[210:213], v[12:15]
	v_mfma_f32_16x16x32_bf16 v[4:7], v[152:155], v[206:209], v[4:7]
	v_mfma_f32_16x16x32_bf16 v[4:7], v[156:159], v[210:213], v[4:7]
	s_setprio 0
	s_setprio 1
	v_mfma_f32_16x16x32_bf16 v[56:59], v[160:163], v[182:185], v[56:59]
	v_mfma_f32_16x16x32_bf16 v[56:59], v[170:173], v[186:189], v[56:59]
	v_mfma_f32_16x16x32_bf16 v[48:51], v[174:177], v[182:185], v[48:51]
	v_mfma_f32_16x16x32_bf16 v[48:51], v[178:181], v[186:189], v[48:51]
	v_mfma_f32_16x16x32_bf16 v[40:43], v[160:163], v[190:193], v[40:43]
	v_mfma_f32_16x16x32_bf16 v[40:43], v[170:173], v[194:197], v[40:43]
	v_mfma_f32_16x16x32_bf16 v[32:35], v[174:177], v[190:193], v[32:35]
	v_mfma_f32_16x16x32_bf16 v[32:35], v[178:181], v[194:197], v[32:35]
	v_mfma_f32_16x16x32_bf16 v[24:27], v[160:163], v[198:201], v[24:27]
	v_mfma_f32_16x16x32_bf16 v[24:27], v[170:173], v[202:205], v[24:27]
	v_mfma_f32_16x16x32_bf16 v[16:19], v[174:177], v[198:201], v[16:19]
	v_mfma_f32_16x16x32_bf16 v[16:19], v[178:181], v[202:205], v[16:19]
	v_mfma_f32_16x16x32_bf16 v[8:11], v[160:163], v[206:209], v[8:11]
	v_mfma_f32_16x16x32_bf16 v[8:11], v[170:173], v[210:213], v[8:11]
	v_mfma_f32_16x16x32_bf16 v[0:3], v[174:177], v[206:209], v[0:3]
	v_mfma_f32_16x16x32_bf16 v[0:3], v[178:181], v[210:213], v[0:3]
	s_setprio 0
	s_barrier
	s_add_i32 s62, s62, 2
	s_add_u32 s36, s36, 0x10000
	s_addc_u32 s37, s37, 0
	s_add_u32 s44, s44, 0x10000
	s_addc_u32 s45, s45, 0
	s_cmp_gt_u32 s62, 29
	s_cbranch_scc0 .LBB0_263
	s_and_b64 vcc, exec, s[8:9]
	s_cbranch_vccz .LBB0_266
	s_barrier
